# k20: k19 + compiler-inserted per-iteration vmcnt(0) removed from the QKV GEMM K-loop head
# speedup vs baseline: 1.0236x; 1.0052x over previous
; #define PG8_STAGE(bufoff, gbase, voff) do { _Pragma("unroll") for (int _i = 0; _i < 2; ++_i) \
;         __builtin_amdgcn_global_load_lds((const unsigned*)((const char*)(gbase) + (voff)[_i]), (LAS unsigned*)(lds + (bufoff) + ldsw + _i * 8192), 16, 0, 0); } while (0)
; #define PG8_LDA(dst, b, h) do { _Pragma("unroll") for (int m = 0; m < 4; ++m) _Pragma("unroll") for (int k = 0; k < 2; ++k) dst[m][k] = *(const LAS bf16x8*)(lds + PG8_SA(b, h) + aoff + m * 2048 + k * 1024); } while (0)
; #define PG8_LDB(dst, b, h) do { _Pragma("unroll") for (int n = 0; n < 2; ++n) _Pragma("unroll") for (int k = 0; k < 2; ++k) dst[n][k] = *(const LAS bf16x8*)(lds + PG8_SB(b, h) + boff + n * 2048 + k * 1024); } while (0)
; #define PG8_MMA(ai, bj, At, Bt) do { __builtin_amdgcn_s_setprio(1); _Pragma("unroll") for (int m = 0; m < 4; ++m) _Pragma("unroll") for (int n = 0; n < 2; ++n) _Pragma("unroll") for (int k = 0; k < 2; ++k) \
;         acc[ai][bj][m][n] = __builtin_amdgcn_mfma_f32_16x16x32_bf16(Bt[n][k], At[m][k], acc[ai][bj][m][n], 0, 0, 0); __builtin_amdgcn_s_setprio(0); } while (0)
; #define PG8_WAIT_L(n) asm volatile("s_waitcnt lgkmcnt(" #n ")" ::: "memory")
; #define PG8_BAR __builtin_amdgcn_s_barrier()
; #define PG8_SCHED __builtin_amdgcn_sched_barrier(0)
; template <class Epi>
; __device__ __forceinline__ void gemm_phase(LAS unsigned char* lds, const Gemm g, const Epi& E) {
;     ...
;             PG8_LDB(B0, 0, 0); PG8_SCHED; PG8_LDA(At, 0, 0); PG8_STAGE(PG8_SA(1, 1), a1 + hstepA, voffA);
;             PG8_WAIT_L(8); PG8_BAR; PG8_WAIT_L(0); PG8_MMA(0, 0, At, B0); PG8_BAR; PG8_SCHED;
;             PG8_LDB(B1, 0, 1); PG8_STAGE(PG8_SB(0, 0), b2, voffB);
;             PG8_BAR; PG8_WAIT_L(0); PG8_MMA(0, 1, At, B1); PG8_BAR;
;             PG8_LDA(At, 0, 1); PG8_STAGE(PG8_SA(0, 0), a2, voffA);
;             PG8_BAR; PG8_WAIT_L(0); PG8_MMA(1, 0, At, B0); PG8_BAR; PG8_SCHED;
.LBB0_331:
	s_add_u32 s60, s4, 0xfffc0080
	s_addc_u32 s61, s5, -1
	s_add_i32 s72, 0, 0x10000
	v_add_u32_e32 v94, s72, v201
	ds_read_b128 v[74:77], v94
	ds_read_b128 v[82:85], v94 offset:1024
	ds_read_b128 v[86:89], v94 offset:2048
	ds_read_b128 v[94:97], v94 offset:3072
	s_cmp_eq_u32 s53, 12
	s_cselect_b32 s65, s29, s61
	s_cselect_b32 s64, s28, s60
	s_cselect_b32 s61, s59, s52
	s_cselect_b32 s60, s58, s15
	v_lshl_add_u64 v[192:193], s[4:5], 0, v[188:189]
	s_add_i32 m0, s24, 0xc000
	ds_read_b128 v[106:109], v202
	ds_read_b128 v[110:113], v202 offset:1024
	ds_read_b128 v[130:133], v202 offset:2048
	ds_read_b128 v[134:137], v202 offset:3072
	ds_read_b128 v[154:157], v202 offset:4096
	ds_read_b128 v[158:161], v202 offset:5120
	ds_read_b128 v[170:173], v202 offset:6144
	ds_read_b128 v[174:177], v202 offset:7168
	global_load_lds_dwordx4 v[192:193], off
	v_lshl_add_u64 v[192:193], s[4:5], 0, v[190:191]
	s_add_i32 m0, s24, 0xe000
	s_nop 0
	global_load_lds_dwordx4 v[192:193], off
	s_waitcnt lgkmcnt(8)
	s_barrier
	s_waitcnt lgkmcnt(0)
	v_mfma_f32_16x16x32_bf16 v[166:169], v[74:77], v[106:109], v[166:169]
	v_mfma_f32_16x16x32_bf16 v[162:165], v[86:89], v[106:109], v[162:165]
	v_mfma_f32_16x16x32_bf16 v[142:145], v[74:77], v[130:133], v[142:145]
	v_mfma_f32_16x16x32_bf16 v[138:141], v[86:89], v[130:133], v[138:141]
	v_mfma_f32_16x16x32_bf16 v[118:121], v[74:77], v[154:157], v[118:121]
	v_mfma_f32_16x16x32_bf16 v[114:117], v[86:89], v[154:157], v[114:117]
	v_mfma_f32_16x16x32_bf16 v[90:93], v[74:77], v[170:173], v[90:93]
	v_mfma_f32_16x16x32_bf16 v[78:81], v[86:89], v[170:173], v[78:81]
	v_mfma_f32_16x16x32_bf16 v[166:169], v[82:85], v[110:113], v[166:169]
	v_mfma_f32_16x16x32_bf16 v[162:165], v[94:97], v[110:113], v[162:165]
	v_mfma_f32_16x16x32_bf16 v[142:145], v[82:85], v[134:137], v[142:145]
	v_mfma_f32_16x16x32_bf16 v[138:141], v[94:97], v[134:137], v[138:141]
	v_mfma_f32_16x16x32_bf16 v[118:121], v[82:85], v[158:161], v[118:121]
	v_mfma_f32_16x16x32_bf16 v[114:117], v[94:97], v[158:161], v[114:117]
	v_mfma_f32_16x16x32_bf16 v[90:93], v[82:85], v[174:177], v[90:93]
	v_mfma_f32_16x16x32_bf16 v[78:81], v[94:97], v[174:177], v[78:81]
	s_barrier
	s_add_i32 s74, 0, 0x14000
	s_add_i32 s72, s72, s1
	v_add_u32_e32 v203, s74, v201
	v_lshl_add_u64 v[208:209], s[60:61], 0, v[184:185]
	s_mov_b32 m0, s72
	ds_read_b128 v[192:195], v203
	ds_read_b128 v[196:199], v203 offset:1024
	ds_read_b128 v[204:207], v203 offset:2048
	ds_read_b128 v[226:229], v203 offset:3072
	global_load_lds_dwordx4 v[208:209], off
	v_lshl_add_u64 v[234:235], s[60:61], 0, v[180:181]
	s_add_i32 m0, s72, 0x2000
	s_nop 0
	global_load_lds_dwordx4 v[234:235], off
	s_nop 1
	s_mov_b32 m0, s24
	v_lshl_add_u64 v[236:237], s[64:65], 0, v[186:187]
	s_barrier
	s_waitcnt lgkmcnt(0)
	v_mfma_f32_16x16x32_bf16 v[150:153], v[192:195], v[106:109], v[150:153]
	v_mfma_f32_16x16x32_bf16 v[106:109], v[204:207], v[106:109], v[146:149]
	v_mfma_f32_16x16x32_bf16 v[122:125], v[204:207], v[130:133], v[122:125]
	v_mfma_f32_16x16x32_bf16 v[102:105], v[192:195], v[154:157], v[102:105]
	v_mfma_f32_16x16x32_bf16 v[98:101], v[204:207], v[154:157], v[98:101]
	v_mfma_f32_16x16x32_bf16 v[70:73], v[192:195], v[170:173], v[70:73]
	v_mfma_f32_16x16x32_bf16 v[66:69], v[204:207], v[170:173], v[66:69]
	v_mfma_f32_16x16x32_bf16 v[150:153], v[196:199], v[110:113], v[150:153]
	v_mfma_f32_16x16x32_bf16 v[106:109], v[226:229], v[110:113], v[106:109]
	v_mfma_f32_16x16x32_bf16 v[110:113], v[192:195], v[130:133], v[126:129]
	v_mfma_f32_16x16x32_bf16 v[122:125], v[226:229], v[134:137], v[122:125]
	v_mfma_f32_16x16x32_bf16 v[102:105], v[196:199], v[158:161], v[102:105]
	v_mfma_f32_16x16x32_bf16 v[98:101], v[226:229], v[158:161], v[98:101]
	v_mfma_f32_16x16x32_bf16 v[70:73], v[196:199], v[174:177], v[70:73]
	v_mfma_f32_16x16x32_bf16 v[66:69], v[226:229], v[174:177], v[66:69]
	v_mfma_f32_16x16x32_bf16 v[110:113], v[196:199], v[134:137], v[110:113]
	s_barrier
	ds_read_b128 v[126:129], v202 offset:16384
	ds_read_b128 v[130:133], v202 offset:17408
	ds_read_b128 v[134:137], v202 offset:18432
	ds_read_b128 v[146:149], v202 offset:19456
	ds_read_b128 v[154:157], v202 offset:20480
	ds_read_b128 v[158:161], v202 offset:21504
	ds_read_b128 v[170:173], v202 offset:22528
	ds_read_b128 v[174:177], v202 offset:23552
	global_load_lds_dwordx4 v[236:237], off
	v_lshl_add_u64 v[238:239], s[64:65], 0, v[182:183]
	s_mov_b32 m0, s25
	s_nop 0
	global_load_lds_dwordx4 v[238:239], off
	s_barrier
	s_waitcnt lgkmcnt(0)
	v_mfma_f32_16x16x32_bf16 v[62:65], v[74:77], v[126:129], v[62:65]
	v_mfma_f32_16x16x32_bf16 v[58:61], v[86:89], v[126:129], v[58:61]
	v_mfma_f32_16x16x32_bf16 v[46:49], v[74:77], v[134:137], v[46:49]
	v_mfma_f32_16x16x32_bf16 v[42:45], v[86:89], v[134:137], v[42:45]
	v_mfma_f32_16x16x32_bf16 v[30:33], v[74:77], v[154:157], v[30:33]
	v_mfma_f32_16x16x32_bf16 v[26:29], v[86:89], v[154:157], v[26:29]
	v_mfma_f32_16x16x32_bf16 v[14:17], v[74:77], v[170:173], v[14:17]
	v_mfma_f32_16x16x32_bf16 v[10:13], v[86:89], v[170:173], v[10:13]
	v_mfma_f32_16x16x32_bf16 v[62:65], v[82:85], v[130:133], v[62:65]
	v_mfma_f32_16x16x32_bf16 v[58:61], v[94:97], v[130:133], v[58:61]
	v_mfma_f32_16x16x32_bf16 v[46:49], v[82:85], v[146:149], v[46:49]
	v_mfma_f32_16x16x32_bf16 v[42:45], v[94:97], v[146:149], v[42:45]
	v_mfma_f32_16x16x32_bf16 v[30:33], v[82:85], v[158:161], v[30:33]
	v_mfma_f32_16x16x32_bf16 v[26:29], v[94:97], v[158:161], v[26:29]
	v_mfma_f32_16x16x32_bf16 v[14:17], v[82:85], v[174:177], v[14:17]
	v_mfma_f32_16x16x32_bf16 v[10:13], v[94:97], v[174:177], v[10:13]
	s_barrier
; #define PG8_STAGE(bufoff, gbase, voff) do { _Pragma("unroll") for (int _i = 0; _i < 2; ++_i) \
;         __builtin_amdgcn_global_load_lds((const unsigned*)((const char*)(gbase) + (voff)[_i]), (LAS unsigned*)(lds + (bufoff) + ldsw + _i * 8192), 16, 0, 0); } while (0)
; #define PG8_LDA(dst, b, h) do { _Pragma("unroll") for (int m = 0; m < 4; ++m) _Pragma("unroll") for (int k = 0; k < 2; ++k) dst[m][k] = *(const LAS bf16x8*)(lds + PG8_SA(b, h) + aoff + m * 2048 + k * 1024); } while (0)
; #define PG8_LDB(dst, b, h) do { _Pragma("unroll") for (int n = 0; n < 2; ++n) _Pragma("unroll") for (int k = 0; k < 2; ++k) dst[n][k] = *(const LAS bf16x8*)(lds + PG8_SB(b, h) + boff + n * 2048 + k * 1024); } while (0)
; #define PG8_MMA(ai, bj, At, Bt) do { __builtin_amdgcn_s_setprio(1); _Pragma("unroll") for (int m = 0; m < 4; ++m) _Pragma("unroll") for (int n = 0; n < 2; ++n) _Pragma("unroll") for (int k = 0; k < 2; ++k) \
;         acc[ai][bj][m][n] = __builtin_amdgcn_mfma_f32_16x16x32_bf16(Bt[n][k], At[m][k], acc[ai][bj][m][n], 0, 0, 0); __builtin_amdgcn_s_setprio(0); } while (0)
; #define PG8_WAIT_V(n) asm volatile("s_waitcnt vmcnt(" #n ")" ::: "memory")
; #define PG8_WAIT_L(n) asm volatile("s_waitcnt lgkmcnt(" #n ")" ::: "memory")
; #define PG8_BAR __builtin_amdgcn_s_barrier()
; #define PG8_SCHED __builtin_amdgcn_sched_barrier(0)
; template <class Epi>
; __device__ __forceinline__ void gemm_phase(LAS unsigned char* lds, const Gemm g, const Epi& E) {
;     ...
;             PG8_STAGE(PG8_SB(0, 1), b2 + hstepB, voffB);
;             PG8_WAIT_V(6); PG8_BAR; PG8_MMA(1, 1, At, B1); PG8_BAR;
;             PG8_LDB(B0, 1, 0); PG8_SCHED; PG8_LDA(At, 1, 0); PG8_STAGE(PG8_SA(0, 1), a2 + hstepA, voffA);
;             PG8_WAIT_L(8); PG8_BAR; PG8_WAIT_L(0); PG8_MMA(0, 0, At, B0); PG8_BAR; PG8_SCHED;
;             PG8_LDB(B1, 1, 1); PG8_STAGE(PG8_SB(1, 0), b3, voffB);
;             PG8_BAR; PG8_WAIT_L(0); PG8_MMA(0, 1, At, B1); PG8_BAR;
	s_add_u32 s72, s60, 0x40000
	s_addc_u32 s73, s61, 0
	s_add_i32 s74, s74, s1
	v_lshl_add_u64 v[74:75], s[72:73], 0, v[184:185]
	s_mov_b32 m0, s74
	s_nop 0
	global_load_lds_dwordx4 v[74:75], off
	v_lshl_add_u64 v[74:75], s[72:73], 0, v[180:181]
	s_add_i32 m0, s74, 0x2000
	s_nop 0
	global_load_lds_dwordx4 v[74:75], off
	s_add_i32 s72, 0, 0x18000
	v_add_u32_e32 v94, s72, v201
	s_waitcnt vmcnt(6)
	s_barrier
	v_mfma_f32_16x16x32_bf16 v[54:57], v[192:195], v[126:129], v[54:57]
	v_mfma_f32_16x16x32_bf16 v[50:53], v[204:207], v[126:129], v[50:53]
	v_mfma_f32_16x16x32_bf16 v[38:41], v[192:195], v[134:137], v[38:41]
	v_mfma_f32_16x16x32_bf16 v[34:37], v[204:207], v[134:137], v[34:37]
	v_mfma_f32_16x16x32_bf16 v[22:25], v[192:195], v[154:157], v[22:25]
	v_mfma_f32_16x16x32_bf16 v[18:21], v[204:207], v[154:157], v[18:21]
	v_mfma_f32_16x16x32_bf16 v[6:9], v[192:195], v[170:173], v[6:9]
	v_mfma_f32_16x16x32_bf16 v[2:5], v[204:207], v[170:173], v[2:5]
	v_mfma_f32_16x16x32_bf16 v[54:57], v[196:199], v[130:133], v[54:57]
	v_mfma_f32_16x16x32_bf16 v[50:53], v[226:229], v[130:133], v[50:53]
	v_mfma_f32_16x16x32_bf16 v[38:41], v[196:199], v[146:149], v[38:41]
	v_mfma_f32_16x16x32_bf16 v[34:37], v[226:229], v[146:149], v[34:37]
	v_mfma_f32_16x16x32_bf16 v[22:25], v[196:199], v[158:161], v[22:25]
	v_mfma_f32_16x16x32_bf16 v[18:21], v[226:229], v[158:161], v[18:21]
	v_mfma_f32_16x16x32_bf16 v[6:9], v[196:199], v[174:177], v[6:9]
	v_mfma_f32_16x16x32_bf16 v[2:5], v[226:229], v[174:177], v[2:5]
	s_barrier
	ds_read_b128 v[74:77], v94
	ds_read_b128 v[82:85], v94 offset:1024
	ds_read_b128 v[86:89], v94 offset:2048
	ds_read_b128 v[94:97], v94 offset:3072
	s_add_u32 s64, s64, 0x40000
	s_addc_u32 s65, s65, 0
	s_mov_b32 m0, s31
	v_lshl_add_u64 v[146:147], s[64:65], 0, v[186:187]
	ds_read_b128 v[126:129], v202 offset:32768
	ds_read_b128 v[130:133], v202 offset:33792
	ds_read_b128 v[134:137], v202 offset:34816
	ds_read_b128 v[154:157], v202 offset:35840
	ds_read_b128 v[158:161], v202 offset:36864
	ds_read_b128 v[170:173], v202 offset:37888
	ds_read_b128 v[174:177], v202 offset:38912
	ds_read_b128 v[192:195], v202 offset:39936
	global_load_lds_dwordx4 v[146:147], off
	v_lshl_add_u64 v[146:147], s[64:65], 0, v[182:183]
	s_mov_b32 m0, s36
	s_nop 0
	global_load_lds_dwordx4 v[146:147], off
	s_waitcnt lgkmcnt(8)
	s_barrier
	s_waitcnt lgkmcnt(0)
	v_mfma_f32_16x16x32_bf16 v[146:149], v[74:77], v[126:129], v[166:169]
	v_mfma_f32_16x16x32_bf16 v[166:169], v[82:85], v[130:133], v[146:149]
	v_mfma_f32_16x16x32_bf16 v[146:149], v[86:89], v[126:129], v[162:165]
	v_mfma_f32_16x16x32_bf16 v[142:145], v[74:77], v[134:137], v[142:145]
	v_mfma_f32_16x16x32_bf16 v[138:141], v[86:89], v[134:137], v[138:141]
	v_mfma_f32_16x16x32_bf16 v[118:121], v[74:77], v[158:161], v[118:121]
	v_mfma_f32_16x16x32_bf16 v[114:117], v[86:89], v[158:161], v[114:117]
	v_mfma_f32_16x16x32_bf16 v[90:93], v[74:77], v[174:177], v[90:93]
	v_mfma_f32_16x16x32_bf16 v[78:81], v[86:89], v[174:177], v[78:81]
	v_mfma_f32_16x16x32_bf16 v[162:165], v[94:97], v[130:133], v[146:149]
	v_mfma_f32_16x16x32_bf16 v[142:145], v[82:85], v[154:157], v[142:145]
	v_mfma_f32_16x16x32_bf16 v[138:141], v[94:97], v[154:157], v[138:141]
	v_mfma_f32_16x16x32_bf16 v[118:121], v[82:85], v[170:173], v[118:121]
	v_mfma_f32_16x16x32_bf16 v[114:117], v[94:97], v[170:173], v[114:117]
	v_mfma_f32_16x16x32_bf16 v[90:93], v[82:85], v[192:195], v[90:93]
	v_mfma_f32_16x16x32_bf16 v[78:81], v[94:97], v[192:195], v[78:81]
	s_barrier
	s_add_i32 s64, 0, 0x1c000
	v_add_u32_e32 v146, s64, v201
	s_add_i32 s65, s72, s1
	ds_read_b128 v[196:199], v146
	ds_read_b128 v[204:207], v146 offset:1024
	ds_read_b128 v[226:229], v146 offset:2048
	ds_read_b128 v[230:233], v146 offset:3072
	v_lshl_add_u64 v[146:147], v[208:209], 0, s[86:87]
	s_mov_b32 m0, s65
	s_nop 0
	global_load_lds_dwordx4 v[146:147], off
	v_lshl_add_u64 v[146:147], v[234:235], 0, s[86:87]
	s_add_i32 m0, s65, 0x2000
	s_nop 0
	global_load_lds_dwordx4 v[146:147], off
	s_barrier
	s_waitcnt lgkmcnt(0)
	v_mfma_f32_16x16x32_bf16 v[146:149], v[196:199], v[126:129], v[150:153]
	v_mfma_f32_16x16x32_bf16 v[106:109], v[226:229], v[126:129], v[106:109]
	v_mfma_f32_16x16x32_bf16 v[150:153], v[204:207], v[130:133], v[146:149]
	v_mfma_f32_16x16x32_bf16 v[146:149], v[230:233], v[130:133], v[106:109]
	v_mfma_f32_16x16x32_bf16 v[106:109], v[196:199], v[134:137], v[110:113]
	v_mfma_f32_16x16x32_bf16 v[126:129], v[204:207], v[154:157], v[106:109]
	v_mfma_f32_16x16x32_bf16 v[106:109], v[226:229], v[134:137], v[122:125]
	v_mfma_f32_16x16x32_bf16 v[102:105], v[196:199], v[158:161], v[102:105]
	v_mfma_f32_16x16x32_bf16 v[98:101], v[226:229], v[158:161], v[98:101]
	v_mfma_f32_16x16x32_bf16 v[70:73], v[196:199], v[174:177], v[70:73]
	v_mfma_f32_16x16x32_bf16 v[66:69], v[226:229], v[174:177], v[66:69]
	v_mfma_f32_16x16x32_bf16 v[122:125], v[230:233], v[154:157], v[106:109]
	v_mfma_f32_16x16x32_bf16 v[102:105], v[204:207], v[170:173], v[102:105]
	v_mfma_f32_16x16x32_bf16 v[98:101], v[230:233], v[170:173], v[98:101]
	v_mfma_f32_16x16x32_bf16 v[70:73], v[204:207], v[192:195], v[70:73]
	v_mfma_f32_16x16x32_bf16 v[66:69], v[230:233], v[192:195], v[66:69]
	s_mov_b32 m0, s50
	v_lshl_add_u64 v[192:193], v[236:237], 0, s[86:87]
	s_barrier
; #define PG8_STAGE(bufoff, gbase, voff) do { _Pragma("unroll") for (int _i = 0; _i < 2; ++_i) \
;         __builtin_amdgcn_global_load_lds((const unsigned*)((const char*)(gbase) + (voff)[_i]), (LAS unsigned*)(lds + (bufoff) + ldsw + _i * 8192), 16, 0, 0); } while (0)
; #define PG8_LDA(dst, b, h) do { _Pragma("unroll") for (int m = 0; m < 4; ++m) _Pragma("unroll") for (int k = 0; k < 2; ++k) dst[m][k] = *(const LAS bf16x8*)(lds + PG8_SA(b, h) + aoff + m * 2048 + k * 1024); } while (0)
; #define PG8_MMA(ai, bj, At, Bt) do { __builtin_amdgcn_s_setprio(1); _Pragma("unroll") for (int m = 0; m < 4; ++m) _Pragma("unroll") for (int n = 0; n < 2; ++n) _Pragma("unroll") for (int k = 0; k < 2; ++k) \
;         acc[ai][bj][m][n] = __builtin_amdgcn_mfma_f32_16x16x32_bf16(Bt[n][k], At[m][k], acc[ai][bj][m][n], 0, 0, 0); __builtin_amdgcn_s_setprio(0); } while (0)
; #define PG8_WAIT_V(n) asm volatile("s_waitcnt vmcnt(" #n ")" ::: "memory")
; template <class Epi>
; __device__ __forceinline__ void gemm_phase(LAS unsigned char* lds, const Gemm g, const Epi& E) {
;     ...
;             PG8_LDA(At, 1, 1); PG8_STAGE(PG8_SA(1, 0), a3, voffA);
;             PG8_BAR; PG8_WAIT_L(0); PG8_MMA(1, 0, At, B0); PG8_BAR; PG8_SCHED;
;             PG8_STAGE(PG8_SB(1, 1), b3 + hstepB, voffB);
;             PG8_WAIT_V(6); PG8_BAR; PG8_MMA(1, 1, At, B1); PG8_BAR;
;     __device__ __forceinline__ void operator()(const AccT& acc, const Unit& u, int wr, int wc, int fr, int fq) const {
;     ...
;         const int gpm = mapA.src(u.pm);
;         const bool isq = u.pn < 4, isv = u.pn >= 8;
;         const bool lat = gpm >= 32 && !isv;
;         bf16_t* base = isq ? Q : (isv ? Vv + (size_t)(u.pn - 8) * 256 : Kk);
;         const int hh = isv ? 0 : (u.pn & 3);
;         const int ldo = isv ? 2048 : 1024;
;         const float osc = isq ? 0.0625f : 1.0f;
;         const int p0 = 16 * wc + 4 * fq;
;         f32x4 ctR[2][2], ctC[4][2];
;         if (lat) {
; #pragma unroll
;             for (int ai = 0; ai < 2; ++ai) { const int pr = ((gpm - 32) * 4 + 2 * ai + wr) & 31;
;                 ctR[ai][0] = *(const f32x4*)(cs + pr * 64 + p0); ctR[ai][1] = *(const f32x4*)(cs + pr * 64 + p0 + 2); }
; #pragma unroll
;             for (int m = 0; m < 4; ++m) { const int pc = m * 16 + fr;
;                 ctC[m][0] = *(const f32x4*)(cs + pc * 64 + p0); ctC[m][1] = *(const f32x4*)(cs + pc * 64 + p0 + 2); }
;         }
	ds_read_b128 v[106:109], v202 offset:49152
	ds_read_b128 v[110:113], v202 offset:50176
	ds_read_b128 v[130:133], v202 offset:51200
	ds_read_b128 v[134:137], v202 offset:52224
	ds_read_b128 v[154:157], v202 offset:53248
	ds_read_b128 v[158:161], v202 offset:54272
	ds_read_b128 v[170:173], v202 offset:55296
	ds_read_b128 v[174:177], v202 offset:56320
	global_load_lds_dwordx4 v[192:193], off
	v_lshl_add_u64 v[192:193], v[238:239], 0, s[86:87]
	s_mov_b32 m0, s66
	s_nop 0
	global_load_lds_dwordx4 v[192:193], off
	s_barrier
	s_waitcnt lgkmcnt(0)
	v_mfma_f32_16x16x32_bf16 v[62:65], v[74:77], v[106:109], v[62:65]
	v_mfma_f32_16x16x32_bf16 v[58:61], v[86:89], v[106:109], v[58:61]
	v_mfma_f32_16x16x32_bf16 v[46:49], v[74:77], v[130:133], v[46:49]
	v_mfma_f32_16x16x32_bf16 v[42:45], v[86:89], v[130:133], v[42:45]
	v_mfma_f32_16x16x32_bf16 v[30:33], v[74:77], v[154:157], v[30:33]
	v_mfma_f32_16x16x32_bf16 v[26:29], v[86:89], v[154:157], v[26:29]
	v_mfma_f32_16x16x32_bf16 v[14:17], v[74:77], v[170:173], v[14:17]
	v_mfma_f32_16x16x32_bf16 v[10:13], v[86:89], v[170:173], v[10:13]
	v_mfma_f32_16x16x32_bf16 v[62:65], v[82:85], v[110:113], v[62:65]
	v_mfma_f32_16x16x32_bf16 v[58:61], v[94:97], v[110:113], v[58:61]
	v_mfma_f32_16x16x32_bf16 v[46:49], v[82:85], v[134:137], v[46:49]
	v_mfma_f32_16x16x32_bf16 v[42:45], v[94:97], v[134:137], v[42:45]
	v_mfma_f32_16x16x32_bf16 v[30:33], v[82:85], v[158:161], v[30:33]
	v_mfma_f32_16x16x32_bf16 v[26:29], v[94:97], v[158:161], v[26:29]
	v_mfma_f32_16x16x32_bf16 v[14:17], v[82:85], v[174:177], v[14:17]
	v_mfma_f32_16x16x32_bf16 v[10:13], v[94:97], v[174:177], v[10:13]
	s_barrier
	s_add_u32 s60, s60, 0x40080
	s_addc_u32 s61, s61, 0
	s_add_i32 s64, s64, s1
	v_lshl_add_u64 v[74:75], s[60:61], 0, v[184:185]
	s_mov_b32 m0, s64
	s_nop 0
	global_load_lds_dwordx4 v[74:75], off
	v_lshl_add_u64 v[74:75], s[60:61], 0, v[180:181]
	s_add_i32 m0, s64, 0x2000
	s_nop 0
	global_load_lds_dwordx4 v[74:75], off
	s_add_i32 s53, s53, 2
	s_add_u32 s4, s4, 0x100
	s_addc_u32 s5, s5, 0
	s_add_u32 s15, s15, 0x100
	s_addc_u32 s52, s52, 0
	s_cmp_gt_u32 s53, 13
	s_waitcnt vmcnt(6)
	s_barrier
	v_mfma_f32_16x16x32_bf16 v[54:57], v[196:199], v[106:109], v[54:57]
	v_mfma_f32_16x16x32_bf16 v[50:53], v[226:229], v[106:109], v[50:53]
	v_mfma_f32_16x16x32_bf16 v[38:41], v[196:199], v[130:133], v[38:41]
	v_mfma_f32_16x16x32_bf16 v[34:37], v[226:229], v[130:133], v[34:37]
	v_mfma_f32_16x16x32_bf16 v[22:25], v[196:199], v[154:157], v[22:25]
	v_mfma_f32_16x16x32_bf16 v[18:21], v[226:229], v[154:157], v[18:21]
	v_mfma_f32_16x16x32_bf16 v[6:9], v[196:199], v[170:173], v[6:9]
	v_mfma_f32_16x16x32_bf16 v[2:5], v[226:229], v[170:173], v[2:5]
	v_mfma_f32_16x16x32_bf16 v[54:57], v[204:207], v[110:113], v[54:57]
	v_mfma_f32_16x16x32_bf16 v[50:53], v[230:233], v[110:113], v[50:53]
	v_mfma_f32_16x16x32_bf16 v[38:41], v[204:207], v[134:137], v[38:41]
	v_mfma_f32_16x16x32_bf16 v[34:37], v[230:233], v[134:137], v[34:37]
	v_mfma_f32_16x16x32_bf16 v[22:25], v[204:207], v[158:161], v[22:25]
	v_mfma_f32_16x16x32_bf16 v[18:21], v[230:233], v[158:161], v[18:21]
	v_mfma_f32_16x16x32_bf16 v[6:9], v[204:207], v[174:177], v[6:9]
	v_mfma_f32_16x16x32_bf16 v[2:5], v[230:233], v[174:177], v[2:5]
	s_barrier
	s_cbranch_scc0 .LBB0_331
	s_cmp_lt_i32 s10, 16
	s_cselect_b32 s4, s68, s18
	s_add_i32 s15, s10, s4
	s_cmp_lt_i32 s11, 8
	s_cselect_b64 s[60:61], -1, 0
	s_cmp_gt_i32 s15, 31
	s_cselect_b64 s[4:5], -1, 0
	s_and_b64 s[52:53], s[60:61], s[4:5]
	v_cndmask_b32_e64 v74, 0, 1, s[52:53]
	v_mov_b32_e32 v194, v200
	v_mov_b32_e32 v193, v1
	v_cmp_ne_u32_e64 s[4:5], 1, v74
	s_andn2_b64 vcc, exec, s[52:53]
	s_cbranch_vccnz .LBB0_334
	v_lshl_add_u32 v74, v193, 2, s67
	v_readlane_b32 s52, v254, 2
	s_lshl_b32 s15, s15, 8
	v_ashrrev_i32_e32 v75, 31, v74
	v_readlane_b32 s53, v254, 3
	s_add_i32 s15, s15, s44
	s_nop 0
	v_lshl_add_u64 v[74:75], v[74:75], 3, s[52:53]
	s_and_b32 s52, s15, 0x7c0
	s_addk_i32 s15, 0x80
	s_lshl_b32 s76, s52, 3
	s_and_b32 s15, s15, 0x7c0
	v_lshl_add_u64 v[76:77], v[74:75], 0, s[76:77]
	s_lshl_b32 s76, s15, 3
	global_load_dwordx4 v[170:173], v[76:77], off offset:16
	global_load_dwordx4 v[174:177], v[76:77], off
	v_lshl_add_u64 v[76:77], v[74:75], 0, s[76:77]
	global_load_dwordx4 v[86:89], v[76:77], off offset:16
	global_load_dwordx4 v[94:97], v[76:77], off
	v_lshlrev_b32_e32 v76, 6, v194
	v_ashrrev_i32_e32 v77, 31, v76
	v_lshl_add_u64 v[82:83], v[76:77], 3, v[74:75]
	global_load_dwordx4 v[154:157], v[82:83], off offset:16
	global_load_dwordx4 v[158:161], v[82:83], off
	v_add_u32_e32 v82, 0x400, v76
	v_ashrrev_i32_e32 v83, 31, v82
	v_lshl_add_u64 v[82:83], v[82:83], 3, v[74:75]
	global_load_dwordx4 v[130:133], v[82:83], off offset:16
	global_load_dwordx4 v[134:137], v[82:83], off
	v_add_u32_e32 v82, 0x800, v76
	v_ashrrev_i32_e32 v83, 31, v82
	v_add_u32_e32 v76, 0xc00, v76
	v_lshl_add_u64 v[82:83], v[82:83], 3, v[74:75]
	v_ashrrev_i32_e32 v77, 31, v76
	global_load_dwordx4 v[106:109], v[82:83], off offset:16
	global_load_dwordx4 v[110:113], v[82:83], off
	v_lshl_add_u64 v[82:83], v[76:77], 3, v[74:75]
	global_load_dwordx4 v[74:77], v[82:83], off offset:16
	s_nop 0
	global_load_dwordx4 v[82:85], v[82:83], off
